# non-temporal hint on the read-once streams: x f32 rows in phase 0 and the residual rows in the final rmsnorm
# speedup vs baseline: 1.0131x; 1.0131x over previous
; __device__ __forceinline__ int tid_fresh() { int t = threadIdx.x; asm volatile("" : "+v"(t)); return t; }
; __device__ __forceinline__ int bid_fresh() { int t = blockIdx.x; asm volatile("" : "+s"(t)); return t; }
; __device__ __forceinline__ unsigned pk2(float lo, float hi) { const hf32x2 v = {lo, hi}; return __builtin_bit_cast(unsigned, __builtin_convertvector(v, hbf16x2)); }
; __device__ __forceinline__ void phase0(PP p, unsigned char* shm) {
;     ...
;         const int lane = tid_fresh() & 63, gw = bid_fresh() * 8 + (tid_fresh() >> 6), NGW = gridDim.x * 8;
;         float* ssb = (float*)(ws + WS_SS);
;         for (int r = gw; r < T; r += NGW) {
;             const float* x = p->in[0] + (size_t)r * D; bf16_t* o = (bf16_t*)(ws + WS_XN) + (size_t)r * D; float sq = 0.f;
; #pragma unroll
;             for (int j = 0; j < 8; ++j) { const f32x4 v = ((const f32x4*)x)[lane + 64 * j]; sq += v[0] * v[0] + v[1] * v[1] + v[2] * v[2] + v[3] * v[3];
;                 u32x2 w; w.x = pk2(v[0], v[1]); w.y = pk2(v[2], v[3]); ((u32x2*)o)[lane + 64 * j] = w; }
;             sq = wave_sum(sq);
;             if (lane < 32) ssb[(size_t)r * 32 + lane] = (lane == 0) ? sq : 0.f;
;         }
;     }
.LBB0_82:
	v_add_co_u32_e32 v22, vcc, 0xfffff000, v2
	s_nop 1
	v_addc_co_u32_e32 v23, vcc, -1, v3, vcc
	s_waitcnt lgkmcnt(0)
	global_load_dwordx4 v[14:17], v[22:23], off offset:-3072 nt
	global_load_dwordx4 v[18:21], v[22:23], off offset:-2048 nt
	global_load_dwordx4 v[48:51], v[22:23], off offset:-1024 nt
	global_load_dwordx4 v[28:31], v[2:3], off offset:-4096 nt
	global_load_dwordx4 v[32:35], v[2:3], off offset:-3072 nt
	global_load_dwordx4 v[36:39], v[2:3], off offset:-2048 nt
	global_load_dwordx4 v[40:43], v[2:3], off offset:-1024 nt
	global_load_dwordx4 v[44:47], v[2:3], off nt
	s_waitcnt vmcnt(7)
	v_cvt_pk_bf16_f32 v52, v14, v15
	v_cvt_pk_bf16_f32 v53, v16, v17
	global_store_dwordx2 v[4:5], v[52:53], off offset:-2048
	v_mul_f32_e32 v13, v15, v15
	v_fmac_f32_e32 v13, v14, v14
	v_fmac_f32_e32 v13, v16, v16
	v_fmac_f32_e32 v13, v17, v17
	s_waitcnt vmcnt(7)
	v_cvt_pk_bf16_f32 v54, v18, v19
	v_cvt_pk_bf16_f32 v55, v20, v21
	global_store_dwordx2 v[4:5], v[54:55], off offset:-1536
	v_mul_f32_e32 v24, v19, v19
	v_fmac_f32_e32 v24, v18, v18
	v_fmac_f32_e32 v24, v20, v20
	v_fmac_f32_e32 v24, v21, v21
	v_add_f32_e32 v13, v13, v24
	s_waitcnt vmcnt(7)
	v_cvt_pk_bf16_f32 v56, v48, v49
	v_cvt_pk_bf16_f32 v57, v50, v51
	global_store_dwordx2 v[4:5], v[56:57], off offset:-1024
	v_mul_f32_e32 v24, v49, v49
	v_fmac_f32_e32 v24, v48, v48
	v_fmac_f32_e32 v24, v50, v50
	v_fmac_f32_e32 v24, v51, v51
	v_add_f32_e32 v13, v13, v24
	s_waitcnt vmcnt(7)
	v_cvt_pk_bf16_f32 v58, v28, v29
	v_cvt_pk_bf16_f32 v59, v30, v31
	global_store_dwordx2 v[4:5], v[58:59], off offset:-512
	v_mul_f32_e32 v24, v29, v29
	v_fmac_f32_e32 v24, v28, v28
	v_fmac_f32_e32 v24, v30, v30
	v_fmac_f32_e32 v24, v31, v31
	v_add_f32_e32 v13, v13, v24
	s_waitcnt vmcnt(7)
	v_cvt_pk_bf16_f32 v60, v32, v33
	v_cvt_pk_bf16_f32 v61, v34, v35
	global_store_dwordx2 v[4:5], v[60:61], off
	v_mul_f32_e32 v24, v33, v33
	v_fmac_f32_e32 v24, v32, v32
	v_fmac_f32_e32 v24, v34, v34
	v_fmac_f32_e32 v24, v35, v35
	v_add_f32_e32 v13, v13, v24
	s_waitcnt vmcnt(7)
	v_cvt_pk_bf16_f32 v62, v36, v37
	v_cvt_pk_bf16_f32 v63, v38, v39
	global_store_dwordx2 v[4:5], v[62:63], off offset:512
	v_mul_f32_e32 v24, v37, v37
	v_fmac_f32_e32 v24, v36, v36
	v_fmac_f32_e32 v24, v38, v38
	v_fmac_f32_e32 v24, v39, v39
	v_add_f32_e32 v13, v13, v24
	s_waitcnt vmcnt(7)
	v_cvt_pk_bf16_f32 v64, v40, v41
	v_cvt_pk_bf16_f32 v65, v42, v43
	global_store_dwordx2 v[4:5], v[64:65], off offset:1024
	v_mul_f32_e32 v24, v41, v41
	v_fmac_f32_e32 v24, v40, v40
	v_fmac_f32_e32 v24, v42, v42
	v_fmac_f32_e32 v24, v43, v43
	v_add_f32_e32 v13, v13, v24
	s_waitcnt vmcnt(7)
	v_cvt_pk_bf16_f32 v66, v44, v45
	v_cvt_pk_bf16_f32 v67, v46, v47
	global_store_dwordx2 v[4:5], v[66:67], off offset:1536
	v_mul_f32_e32 v24, v45, v45
	v_fmac_f32_e32 v24, v44, v44
	v_fmac_f32_e32 v24, v46, v46
	v_fmac_f32_e32 v24, v47, v47
	v_add_f32_e32 v13, v13, v24
	ds_bpermute_b32 v14, v7, v13
	s_waitcnt lgkmcnt(0)
	v_add_f32_e32 v13, v13, v14
	ds_bpermute_b32 v14, v8, v13
	s_waitcnt lgkmcnt(0)
	v_add_f32_e32 v13, v13, v14
	ds_bpermute_b32 v14, v9, v13
	s_waitcnt lgkmcnt(0)
	v_add_f32_e32 v13, v13, v14
	ds_bpermute_b32 v14, v10, v13
	s_waitcnt lgkmcnt(0)
	v_add_f32_e32 v13, v13, v14
	ds_bpermute_b32 v14, v11, v13
	s_waitcnt lgkmcnt(0)
	v_add_f32_e32 v13, v13, v14
	ds_bpermute_b32 v14, v12, v13
	s_and_saveexec_b64 s[22:23], s[4:5]
	s_cbranch_execz .LBB0_81
	s_waitcnt lgkmcnt(0)
	v_add_f32_e32 v13, v13, v14
	v_cndmask_b32_e64 v13, 0, v13, s[6:7]
	global_store_dword v[0:1], v13, off
	s_branch .LBB0_81

; __global__ void __launch_bounds__(512, 2) hymba_fwd(Params p_unused) {
;     ...
;         for (int r = gw; r < T; r += NGW) {
;             float v[4][8]; float sq = 0.f;
; #pragma unroll
;             for (int j = 0; j < 4; ++j) { float a[8]; unpack8(*(const u32x4*)(hb + (size_t)r * D + (lane + 64 * j) * 8), a);
;                 const u32x2 b = *(const u32x2*)(hl + (size_t)r * D + (lane + 64 * j) * 8);
;                 const hf32x2 l01 = __builtin_amdgcn_cvt_pk_f32_fp8((int)b.x, false), l23 = __builtin_amdgcn_cvt_pk_f32_fp8((int)b.x, true), l45 = __builtin_amdgcn_cvt_pk_f32_fp8((int)b.y, false), l67 = __builtin_amdgcn_cvt_pk_f32_fp8((int)b.y, true);
;                 const float lo[8] = {l01.x, l01.y, l23.x, l23.y, l45.x, l45.y, l67.x, l67.y};
; #pragma unroll
;                 for (int e = 0; e < 8; ++e) { v[j][e] = a[e] + lo[e] * 0.00390625f; sq += v[j][e] * v[j][e]; } }
;             sq = wave_sum(sq);
.LBB0_1498:
	global_load_dwordx2 v[46:47], v[18:19], off offset:-1024 nt
	global_load_dwordx2 v[48:49], v[18:19], off offset:-512 nt
	global_load_dwordx2 v[50:51], v[18:19], off nt
	global_load_dwordx2 v[52:53], v[18:19], off offset:512 nt
	global_load_dwordx4 v[30:33], v[16:17], off offset:1024 nt
	global_load_dwordx4 v[34:37], v[16:17], off offset:-2048 nt
	global_load_dwordx4 v[38:41], v[16:17], off offset:-1024 nt
	global_load_dwordx4 v[42:45], v[16:17], off nt
	v_add_co_u32_e32 v54, vcc, s10, v14
	v_add_u32_e32 v20, s12, v20
	s_nop 0
	v_addc_co_u32_e32 v55, vcc, -1, v15, vcc
	v_lshl_add_u64 v[16:17], v[16:17], 0, s[14:15]
	v_lshl_add_u64 v[18:19], v[18:19], 0, s[4:5]
	s_waitcnt vmcnt(7)
	v_cvt_pk_f32_fp8_e32 v[56:57], v46
	v_cvt_pk_f32_fp8_sdwa v[58:59], v46 src0_sel:WORD_1
	s_waitcnt vmcnt(6)
	v_cvt_pk_f32_fp8_e32 v[66:67], v49
	s_waitcnt vmcnt(4)
	v_cvt_pk_f32_fp8_e32 v[74:75], v52
	v_cvt_pk_f32_fp8_sdwa v[76:77], v52 src0_sel:WORD_1
	v_cvt_pk_f32_fp8_e32 v[78:79], v53
	v_cvt_pk_f32_fp8_sdwa v[52:53], v53 src0_sel:WORD_1
	v_cvt_pk_f32_fp8_e32 v[62:63], v48
	v_cvt_pk_f32_fp8_sdwa v[64:65], v48 src0_sel:WORD_1
	v_cvt_pk_f32_fp8_sdwa v[48:49], v49 src0_sel:WORD_1
	v_cvt_pk_f32_fp8_e32 v[68:69], v50
	v_cvt_pk_f32_fp8_e32 v[60:61], v47
	s_waitcnt vmcnt(3)
	v_lshlrev_b32_e32 v80, 16, v33
	v_and_b32_e32 v81, 0xffff0000, v33
	s_waitcnt vmcnt(2)
	v_lshlrev_b32_e32 v82, 16, v34
	v_and_b32_e32 v83, 0xffff0000, v34
	v_cvt_pk_f32_fp8_sdwa v[70:71], v50 src0_sel:WORD_1
	v_lshlrev_b32_e32 v34, 16, v35
	v_and_b32_e32 v35, 0xffff0000, v35
	s_waitcnt vmcnt(1)
	v_lshlrev_b32_e32 v88, 16, v40
	v_and_b32_e32 v89, 0xffff0000, v40
	v_lshlrev_b32_e32 v96, 16, v32
	v_and_b32_e32 v97, 0xffff0000, v32
	v_pk_fma_f32 v[32:33], v[52:53], s[8:9], v[80:81] op_sel_hi:[1,0,1]
	v_pk_fma_f32 v[52:53], v[56:57], s[8:9], v[82:83] op_sel_hi:[1,0,1]
	v_cvt_pk_f32_fp8_sdwa v[46:47], v47 src0_sel:WORD_1
	v_lshlrev_b32_e32 v40, 16, v41
	v_and_b32_e32 v41, 0xffff0000, v41
	s_waitcnt vmcnt(0)
	v_lshlrev_b32_e32 v90, 16, v42
	v_and_b32_e32 v91, 0xffff0000, v42
	v_pk_fma_f32 v[34:35], v[58:59], s[8:9], v[34:35] op_sel_hi:[1,0,1]
	v_pk_fma_f32 v[58:59], v[66:67], s[8:9], v[88:89] op_sel_hi:[1,0,1]
	v_pk_mul_f32 v[66:67], v[52:53], v[52:53]
	v_cvt_pk_f32_fp8_e32 v[72:73], v51
	v_lshlrev_b32_e32 v84, 16, v36
	v_and_b32_e32 v85, 0xffff0000, v36
	v_pk_fma_f32 v[40:41], v[48:49], s[8:9], v[40:41] op_sel_hi:[1,0,1]
	v_pk_fma_f32 v[48:49], v[68:69], s[8:9], v[90:91] op_sel_hi:[1,0,1]
	v_pk_mul_f32 v[68:69], v[34:35], v[34:35]
	v_add_f32_e32 v29, v66, v67
	v_lshlrev_b32_e32 v42, 16, v43
	v_and_b32_e32 v43, 0xffff0000, v43
	v_pk_fma_f32 v[56:57], v[60:61], s[8:9], v[84:85] op_sel_hi:[1,0,1]
	v_add_f32_e32 v29, v29, v68
	v_cvt_pk_f32_fp8_sdwa v[50:51], v51 src0_sel:WORD_1
	v_lshlrev_b32_e32 v36, 16, v37
	v_and_b32_e32 v37, 0xffff0000, v37
	v_pk_fma_f32 v[42:43], v[70:71], s[8:9], v[42:43] op_sel_hi:[1,0,1]
	v_pk_mul_f32 v[70:71], v[56:57], v[56:57]
	v_add_f32_e32 v29, v29, v69
	v_lshlrev_b32_e32 v92, 16, v44
	v_and_b32_e32 v93, 0xffff0000, v44
	v_pk_fma_f32 v[36:37], v[46:47], s[8:9], v[36:37] op_sel_hi:[1,0,1]
	v_add_f32_e32 v29, v29, v70
	v_lshlrev_b32_e32 v86, 16, v38
	v_and_b32_e32 v87, 0xffff0000, v38
	v_pk_fma_f32 v[60:61], v[72:73], s[8:9], v[92:93] op_sel_hi:[1,0,1]
	v_pk_mul_f32 v[72:73], v[36:37], v[36:37]
	v_add_f32_e32 v29, v29, v71
	v_lshlrev_b32_e32 v44, 16, v45
	v_and_b32_e32 v45, 0xffff0000, v45
	v_lshlrev_b32_e32 v94, 16, v30
	v_and_b32_e32 v95, 0xffff0000, v30
	v_pk_fma_f32 v[46:47], v[62:63], s[8:9], v[86:87] op_sel_hi:[1,0,1]
	v_add_f32_e32 v29, v29, v72
	v_lshlrev_b32_e32 v38, 16, v39
	v_and_b32_e32 v39, 0xffff0000, v39
	v_pk_fma_f32 v[44:45], v[50:51], s[8:9], v[44:45] op_sel_hi:[1,0,1]
	v_pk_fma_f32 v[50:51], v[74:75], s[8:9], v[94:95] op_sel_hi:[1,0,1]
	v_pk_mul_f32 v[74:75], v[46:47], v[46:47]
	v_add_f32_e32 v29, v29, v73
	v_lshlrev_b32_e32 v30, 16, v31
	v_and_b32_e32 v31, 0xffff0000, v31
	v_pk_fma_f32 v[38:39], v[64:65], s[8:9], v[38:39] op_sel_hi:[1,0,1]
	v_add_f32_e32 v29, v29, v74
	v_pk_fma_f32 v[30:31], v[76:77], s[8:9], v[30:31] op_sel_hi:[1,0,1]
	v_pk_mul_f32 v[76:77], v[38:39], v[38:39]
	v_add_f32_e32 v29, v29, v75
	v_add_f32_e32 v29, v29, v76
	v_pk_fma_f32 v[62:63], v[78:79], s[8:9], v[96:97] op_sel_hi:[1,0,1]
	v_pk_mul_f32 v[78:79], v[58:59], v[58:59]
	v_add_f32_e32 v29, v29, v77
	v_add_f32_e32 v29, v29, v78
	v_pk_mul_f32 v[80:81], v[40:41], v[40:41]
	v_add_f32_e32 v29, v29, v79
	v_add_f32_e32 v29, v29, v80
	v_pk_mul_f32 v[82:83], v[48:49], v[48:49]
	v_add_f32_e32 v29, v29, v81
	v_add_f32_e32 v29, v29, v82
	v_pk_mul_f32 v[84:85], v[42:43], v[42:43]
	v_add_f32_e32 v29, v29, v83
	v_add_f32_e32 v29, v29, v84
	v_pk_mul_f32 v[86:87], v[60:61], v[60:61]
	v_add_f32_e32 v29, v29, v85
	v_add_f32_e32 v29, v29, v86
	v_pk_mul_f32 v[88:89], v[44:45], v[44:45]
	v_add_f32_e32 v29, v29, v87
	v_add_f32_e32 v29, v29, v88
	v_pk_mul_f32 v[90:91], v[50:51], v[50:51]
	v_add_f32_e32 v29, v29, v89
	v_add_f32_e32 v29, v29, v90
	v_pk_mul_f32 v[92:93], v[30:31], v[30:31]
	v_add_f32_e32 v29, v29, v91
	v_add_f32_e32 v29, v29, v92
	v_pk_mul_f32 v[94:95], v[62:63], v[62:63]
	v_add_f32_e32 v29, v29, v93
	v_add_f32_e32 v29, v29, v94
	v_pk_mul_f32 v[64:65], v[32:33], v[32:33]
	v_add_f32_e32 v29, v29, v95
	v_add_f32_e32 v29, v29, v64
	v_add_f32_e32 v29, v29, v65
	ds_bpermute_b32 v64, v21, v29
	s_waitcnt lgkmcnt(0)
; __global__ void __launch_bounds__(512, 2) hymba_fwd(Params p_unused) {
;     ...
;             sq = wave_sum(sq);
;             const float rs = 1.0f / sqrtf(sq * (1.0f / D) + EPS);
; #pragma unroll
;             for (int j = 0; j < 4; ++j) { const f32x4 g0 = *(const f32x4*)(gf + (lane + 64 * j) * 8), g1 = *(const f32x4*)(gf + (lane + 64 * j) * 8 + 4);
;                 float* o = outp + (size_t)r * D + (lane + 64 * j) * 8;
;                 *(f32x4*)o = (f32x4){v[j][0] * rs * g0[0], v[j][1] * rs * g0[1], v[j][2] * rs * g0[2], v[j][3] * rs * g0[3]};
;                 *(f32x4*)(o + 4) = (f32x4){v[j][4] * rs * g1[0], v[j][5] * rs * g1[1], v[j][6] * rs * g1[2], v[j][7] * rs * g1[3]}; }
;         }
	v_add_f32_e32 v29, v29, v64
	ds_bpermute_b32 v64, v22, v29
	s_waitcnt lgkmcnt(0)
	v_add_f32_e32 v29, v29, v64
	ds_bpermute_b32 v64, v23, v29
	s_waitcnt lgkmcnt(0)
	v_add_f32_e32 v29, v29, v64
	ds_bpermute_b32 v64, v24, v29
	s_waitcnt lgkmcnt(0)
	v_add_f32_e32 v29, v29, v64
	ds_bpermute_b32 v64, v25, v29
	s_waitcnt lgkmcnt(0)
	v_add_f32_e32 v29, v29, v64
	ds_bpermute_b32 v64, v26, v29
	s_waitcnt lgkmcnt(0)
	v_add_f32_e32 v29, v29, v64
	v_fmamk_f32 v29, v29, 0x3a000000, v27
	v_mul_f32_e32 v64, 0x4f800000, v29
	v_cmp_gt_f32_e32 vcc, s9, v29
	s_nop 1
	v_cndmask_b32_e32 v29, v29, v64, vcc
	v_sqrt_f32_e32 v64, v29
	s_nop 0
	v_add_u32_e32 v65, -1, v64
	v_add_u32_e32 v66, 1, v64
	v_fma_f32 v67, -v65, v64, v29
	v_fma_f32 v68, -v66, v64, v29
	v_cmp_ge_f32_e64 s[0:1], 0, v67
	s_nop 1
	v_cndmask_b32_e64 v64, v64, v65, s[0:1]
	v_cmp_lt_f32_e64 s[0:1], 0, v68
	s_nop 1
	v_cndmask_b32_e64 v64, v64, v66, s[0:1]
	v_mul_f32_e32 v65, 0x37800000, v64
	v_cndmask_b32_e32 v64, v64, v65, vcc
	v_cmp_class_f32_e32 vcc, v29, v28
	s_nop 1
	v_cndmask_b32_e32 v29, v64, v29, vcc
	v_div_scale_f32 v64, s[0:1], v29, v29, 1.0
	v_rcp_f32_e32 v66, v64
	v_div_scale_f32 v65, vcc, 1.0, v29, 1.0
	v_fma_f32 v67, -v64, v66, 1.0
	v_fmac_f32_e32 v66, v67, v66
	v_mul_f32_e32 v67, v65, v66
	v_fma_f32 v68, -v64, v67, v65
	v_fmac_f32_e32 v67, v68, v66
	v_fma_f32 v64, -v64, v67, v65
	v_div_fmas_f32 v64, v64, v66, v67
	v_div_fixup_f32 v64, v64, v29, 1.0
	v_pk_mul_f32 v[52:53], v[64:65], v[52:53] op_sel_hi:[0,1]
	v_pk_mul_f32 v[34:35], v[64:65], v[34:35] op_sel_hi:[0,1]
	v_pk_mul_f32 v[56:57], v[64:65], v[56:57] op_sel_hi:[0,1]
	v_pk_mul_f32 v[36:37], v[64:65], v[36:37] op_sel_hi:[0,1]
	v_pk_mul_f32 v[138:139], v[102:103], v[34:35]
	v_pk_mul_f32 v[136:137], v[100:101], v[52:53]
	v_pk_mul_f32 v[134:135], v[106:107], v[36:37]
	v_pk_mul_f32 v[132:133], v[104:105], v[56:57]
	global_store_dwordx4 v[54:55], v[136:139], off offset:-2064
	global_store_dwordx4 v[54:55], v[132:135], off offset:-2048
	v_pk_mul_f32 v[34:35], v[64:65], v[38:39] op_sel_hi:[0,1]
	v_pk_mul_f32 v[36:37], v[64:65], v[46:47] op_sel_hi:[0,1]
	v_pk_mul_f32 v[38:39], v[64:65], v[40:41] op_sel_hi:[0,1]
	v_pk_mul_f32 v[40:41], v[64:65], v[58:59] op_sel_hi:[0,1]
	v_pk_mul_f32 v[30:31], v[64:65], v[30:31] op_sel_hi:[0,1]
	v_cmp_lt_i32_e32 vcc, s11, v20
	v_pk_mul_f32 v[32:33], v[64:65], v[32:33] op_sel_hi:[0,1]
	s_or_b64 s[6:7], vcc, s[6:7]
	v_pk_mul_f32 v[140:141], v[108:109], v[36:37]
	v_pk_mul_f32 v[142:143], v[110:111], v[34:35]
	v_pk_mul_f32 v[144:145], v[112:113], v[40:41]
	v_pk_mul_f32 v[146:147], v[114:115], v[38:39]
	global_store_dwordx4 v[54:55], v[140:143], off offset:-16
	global_store_dwordx4 v[14:15], v[144:147], off offset:-4096
	v_pk_mul_f32 v[34:35], v[64:65], v[42:43] op_sel_hi:[0,1]
	v_pk_mul_f32 v[36:37], v[64:65], v[48:49] op_sel_hi:[0,1]
	v_pk_mul_f32 v[38:39], v[64:65], v[44:45] op_sel_hi:[0,1]
	v_pk_mul_f32 v[40:41], v[64:65], v[60:61] op_sel_hi:[0,1]
	v_pk_mul_f32 v[148:149], v[116:117], v[36:37]
	v_pk_mul_f32 v[150:151], v[118:119], v[34:35]
	v_pk_mul_f32 v[152:153], v[120:121], v[40:41]
	v_pk_mul_f32 v[154:155], v[122:123], v[38:39]
	global_store_dwordx4 v[14:15], v[148:151], off offset:-2064
	global_store_dwordx4 v[14:15], v[152:155], off offset:-2048
	v_pk_mul_f32 v[34:35], v[64:65], v[50:51] op_sel_hi:[0,1]
	v_pk_mul_f32 v[36:37], v[64:65], v[62:63] op_sel_hi:[0,1]
	v_pk_mul_f32 v[156:157], v[124:125], v[34:35]
	v_pk_mul_f32 v[158:159], v[126:127], v[30:31]
	v_pk_mul_f32 v[160:161], v[128:129], v[36:37]
	v_pk_mul_f32 v[162:163], v[130:131], v[32:33]
	global_store_dwordx4 v[14:15], v[156:159], off offset:-16
	global_store_dwordx4 v[14:15], v[160:163], off
	v_lshl_add_u64 v[14:15], v[14:15], 0, s[2:3]
	s_andn2_b64 exec, exec, s[6:7]
	s_cbranch_execnz .LBB0_1498
